# P8 a_ready hook also touches the first four K-tiles of the unit's A and B tiles (L2 warm-up for the prologue), on top of v100
# baseline (speedup 1.0000x reference)
.LBB0_986:
	s_ashr_i32 s0, s3, 3
	s_add_i32 s0, s5, s0
	s_ashr_i32 s1, s0, 31
	s_lshr_b32 s1, s1, 26
	s_add_i32 s1, s0, s1
	s_ashr_i32 s3, s1, 6
	s_andn2_b32 s1, s1, 63
	s_sub_i32 s0, s0, s1
	s_bfe_i32 s1, s0, 0x80000
	s_bfe_u32 s1, s1, 0x3000c
	s_add_i32 s1, s0, s1
	s_bfe_i32 s4, s1, 0x80000
	s_and_b32 s1, s1, 0xf8
	s_sub_i32 s0, s0, s1
	s_lshl_b32 s3, s3, 3
	s_sext_i32_i16 s4, s4
	s_sext_i32_i8 s0, s0
	s_lshr_b32 s37, s4, 3
	s_add_i32 s3, s3, s0
	s_cmp_gt_i32 s3, 0
	s_cselect_b64 vcc, -1, 0
	s_lshl_b32 s29, s3, 2
	s_or_b32 s38, s29, 2
	s_lshl_b32 s39, s3, 8
	s_add_u32 s12, s20, 0x5800
	s_addc_u32 s13, s21, 0
	s_waitcnt vmcnt(35)
	v_cndmask_b32_e64 v2, 0, 1.0, vcc
	s_add_u32 s16, s18, 0x5800
	v_lshlrev_b32_e32 v148, 3, v0
	s_waitcnt vmcnt(32)
	v_mov_b32_e32 v3, v2
	s_mov_b64 s[6:7], 0x5800
	s_addc_u32 s17, s19, 0
	s_mov_b64 s[10:11], 0
	s_movk_i32 s40, 0x2bf
	s_mov_b32 s41, 0xb000
	s_waitcnt vmcnt(30) lgkmcnt(1)
	v_mov_b64_e32 v[4:5], s[44:45]
	s_movk_i32 s42, 0x2c0
	s_waitcnt vmcnt(28) lgkmcnt(0)
	v_mov_b32_e32 v7, 0
	s_mov_b64 s[22:23], 0xb000
	s_mov_b64 s[30:31], 0x16000
	s_mov_b32 s43, 0x16000
	v_mov_b32_e32 v8, v2
	s_waitcnt vmcnt(26)
	v_mov_b32_e32 v9, v2
	s_movk_i32 s46, 0x5000
	s_movk_i32 s47, 0x2c00
	s_waitcnt vmcnt(24)
	v_mov_b64_e32 v[10:11], s[54:55]
	s_movk_i32 s48, 0x37f
	v_mov_b32_e32 v1, v148
	s_waitcnt vmcnt(21)
	v_mov_b32_e32 v16, v0
	v_readlane_b32 s60, v254, 2
	v_readlane_b32 s62, v254, 0
	v_readlane_b32 s63, v254, 1
	s_sub_u32 s62, s62, 0xc8
	s_subb_u32 s63, s63, 0
	s_load_dwordx4 s[64:67], s[62:63], 0x98
	s_and_b32 s61, s60, 7
	s_lshr_b32 s59, s60, 3
	s_lshl_b32 s61, s61, 5
	s_add_i32 s61, s61, s59
	s_bfe_u32 s98, s61, 0x30003
	s_lshr_b32 s59, s61, 6
	s_and_b32 s61, s61, 7
	s_lshl_b32 s59, s59, 3
	s_add_i32 s60, s59, s61
	s_cmp_lg_u32 s60, 0
	s_cselect_b32 s74, 1.0, 0
	s_mov_b32 s75, s74
	s_mov_b32 s68, 0x3d922279
	s_mov_b32 s70, 0x3fcc422a
	s_mov_b32 s72, 0xbfb8aa3b
	s_lshl_b32 s59, s60, 2
	s_add_u32 s82, s26, 0x18500000
	s_addc_u32 s83, s27, 0
	s_add_i32 s61, s59, 1
	s_max_i32 s61, s61, 0
	s_mul_i32 s61, s61, 0xb000
	s_add_u32 s88, s82, s61
	s_addc_u32 s89, s83, 0
	s_add_i32 s61, s59, 0
	s_max_i32 s61, s61, 0
	s_mul_i32 s61, s61, 0xb000
	s_add_u32 s86, s82, s61
	s_addc_u32 s87, s83, 0
	s_add_i32 s61, s59, -1
	s_max_i32 s61, s61, 0
	s_mul_i32 s61, s61, 0xb000
	s_add_u32 s84, s82, s61
	s_addc_u32 s85, s83, 0
	s_add_i32 s61, s59, -2
	s_max_i32 s61, s61, 0
	s_mul_i32 s61, s61, 0xb000
	s_add_u32 s82, s82, s61
	s_addc_u32 s83, s83, 0
	s_mul_i32 s61, s60, 0x2c0000
	s_add_u32 s90, s26, 0x7d00000
	s_addc_u32 s91, s27, 0
	s_add_u32 s90, s90, s61
	s_addc_u32 s91, s91, 0
	s_add_u32 s92, s90, 0x2c00
	s_addc_u32 s93, s91, 0
	s_waitcnt lgkmcnt(0)
	s_add_u32 s38, s64, 0x0
	s_addc_u32 s39, s65, 0
	s_add_u32 s40, s64, 0xb000
	s_addc_u32 s41, s65, 0
	s_add_u32 s42, s64, 0x16000
	s_addc_u32 s43, s65, 0
	s_mul_i32 s98, s98, 0x2c0000
	s_add_u32 s100, s26, 0x6600000
	s_addc_u32 s101, s27, 0
	s_add_u32 s100, s100, s98
	s_addc_u32 s101, s101, 0
	v_lshrrev_b32_e32 v144, 1, v0
	v_mul_u32_u24_e32 v144, 0x2c00, v144
	v_and_b32_e32 v145, 1, v0
	v_lshl_add_u32 v144, v145, 7, v144
	global_load_dword v138, v144, s[100:101]
	global_load_dword v139, v144, s[100:101] offset:256
	global_load_dword v136, v144, s[90:91]
	global_load_dword v137, v144, s[90:91] offset:256
	v_lshlrev_b32_e32 v2, 5, v0
	v_add_u32_e32 v3, 0x5800, v2
	v_lshlrev_b32_e32 v4, 4, v0
	global_load_dwordx4 v[8:11], v2, s[66:67]
	global_load_dwordx4 v[12:15], v2, s[38:39]
	global_load_dwordx4 v[16:19], v2, s[40:41]
	global_load_dwordx4 v[20:23], v2, s[42:43]
	global_load_dwordx4 v[24:27], v2, s[82:83]
	global_load_dwordx4 v[28:31], v2, s[84:85]
	global_load_dwordx4 v[32:35], v2, s[86:87]
	global_load_dwordx4 v[36:39], v2, s[88:89]
	global_load_dwordx4 v[40:43], v2, s[66:67] offset:16
	global_load_dwordx4 v[44:47], v2, s[38:39] offset:16
	global_load_dwordx4 v[48:51], v2, s[40:41] offset:16
	global_load_dwordx4 v[52:55], v2, s[42:43] offset:16
	global_load_dwordx4 v[56:59], v2, s[82:83] offset:16
	global_load_dwordx4 v[60:63], v2, s[84:85] offset:16
	global_load_dwordx4 v[64:67], v2, s[86:87] offset:16
	global_load_dwordx4 v[68:71], v2, s[88:89] offset:16
	global_load_dwordx4 v[72:75], v3, s[66:67]
	global_load_dwordx4 v[76:79], v3, s[38:39]
	global_load_dwordx4 v[80:83], v3, s[40:41]
	global_load_dwordx4 v[84:87], v3, s[42:43]
	global_load_dwordx4 v[88:91], v3, s[82:83]
	global_load_dwordx4 v[92:95], v3, s[84:85]
	global_load_dwordx4 v[96:99], v3, s[86:87]
	global_load_dwordx4 v[100:103], v3, s[88:89]
	global_load_dwordx4 v[104:107], v3, s[66:67] offset:16
	global_load_dwordx4 v[108:111], v3, s[38:39] offset:16
	global_load_dwordx4 v[112:115], v3, s[40:41] offset:16
	global_load_dwordx4 v[116:119], v3, s[42:43] offset:16
	global_load_dwordx4 v[120:123], v3, s[82:83] offset:16
	global_load_dwordx4 v[124:127], v3, s[84:85] offset:16
	global_load_dwordx4 v[128:131], v3, s[86:87] offset:16
	global_load_dwordx4 v[132:135], v3, s[88:89] offset:16
	s_waitcnt vmcnt(0)
	v_pk_mul_f32 v[136:137], v[12:13], s[74:75] op_sel_hi:[1,0]
	v_pk_mul_f32 v[140:141], v[16:17], s[74:75] op_sel_hi:[1,0]
	v_pk_mul_f32 v[138:139], v[14:15], s[74:75] op_sel_hi:[1,0]
	v_pk_mul_f32 v[142:143], v[18:19], s[74:75] op_sel_hi:[1,0]
	v_pk_fma_f32 v[24:25], v[136:137], v[24:25], v[8:9]
	v_pk_fma_f32 v[8:9], v[136:137], v[28:29], v[8:9]
	v_pk_fma_f32 v[26:27], v[138:139], v[26:27], v[10:11]
	v_pk_fma_f32 v[10:11], v[138:139], v[30:31], v[10:11]
	v_pk_fma_f32 v[24:25], v[140:141], v[28:29], v[24:25]
	v_pk_fma_f32 v[8:9], v[16:17], v[32:33], v[8:9]
	v_pk_fma_f32 v[26:27], v[142:143], v[30:31], v[26:27]
	v_pk_fma_f32 v[10:11], v[18:19], v[34:35], v[10:11]
	v_pk_fma_f32 v[24:25], v[20:21], v[32:33], v[24:25]
	v_pk_fma_f32 v[8:9], v[20:21], v[36:37], v[8:9]
	v_pk_fma_f32 v[26:27], v[22:23], v[34:35], v[26:27]
	v_pk_fma_f32 v[10:11], v[22:23], v[38:39], v[10:11]
	v_pk_mul_f32 v[136:137], v[44:45], s[74:75] op_sel_hi:[1,0]
	v_pk_mul_f32 v[140:141], v[48:49], s[74:75] op_sel_hi:[1,0]
	v_pk_mul_f32 v[138:139], v[46:47], s[74:75] op_sel_hi:[1,0]
	v_pk_mul_f32 v[142:143], v[50:51], s[74:75] op_sel_hi:[1,0]
	v_pk_fma_f32 v[56:57], v[136:137], v[56:57], v[40:41]
	v_pk_fma_f32 v[40:41], v[136:137], v[60:61], v[40:41]
	v_pk_fma_f32 v[58:59], v[138:139], v[58:59], v[42:43]
	v_pk_fma_f32 v[42:43], v[138:139], v[62:63], v[42:43]
	v_pk_fma_f32 v[56:57], v[140:141], v[60:61], v[56:57]
	v_pk_fma_f32 v[40:41], v[48:49], v[64:65], v[40:41]
	v_pk_fma_f32 v[58:59], v[142:143], v[62:63], v[58:59]
	v_pk_fma_f32 v[42:43], v[50:51], v[66:67], v[42:43]
	v_pk_fma_f32 v[56:57], v[52:53], v[64:65], v[56:57]
	v_pk_fma_f32 v[40:41], v[52:53], v[68:69], v[40:41]
	v_pk_fma_f32 v[58:59], v[54:55], v[66:67], v[58:59]
	v_pk_fma_f32 v[42:43], v[54:55], v[70:71], v[42:43]
	v_pk_mul_f32 v[136:137], v[76:77], s[74:75] op_sel_hi:[1,0]
	v_pk_mul_f32 v[140:141], v[80:81], s[74:75] op_sel_hi:[1,0]
	v_pk_mul_f32 v[138:139], v[78:79], s[74:75] op_sel_hi:[1,0]
	v_pk_mul_f32 v[142:143], v[82:83], s[74:75] op_sel_hi:[1,0]
	v_pk_fma_f32 v[88:89], v[136:137], v[88:89], v[72:73]
	v_pk_fma_f32 v[72:73], v[136:137], v[92:93], v[72:73]
	v_pk_fma_f32 v[90:91], v[138:139], v[90:91], v[74:75]
	v_pk_fma_f32 v[74:75], v[138:139], v[94:95], v[74:75]
	v_pk_fma_f32 v[88:89], v[140:141], v[92:93], v[88:89]
	v_pk_fma_f32 v[72:73], v[80:81], v[96:97], v[72:73]
	v_pk_fma_f32 v[90:91], v[142:143], v[94:95], v[90:91]
	v_pk_fma_f32 v[74:75], v[82:83], v[98:99], v[74:75]
	v_pk_fma_f32 v[88:89], v[84:85], v[96:97], v[88:89]
	v_pk_fma_f32 v[72:73], v[84:85], v[100:101], v[72:73]
	v_pk_fma_f32 v[90:91], v[86:87], v[98:99], v[90:91]
	v_pk_fma_f32 v[74:75], v[86:87], v[102:103], v[74:75]
	v_pk_mul_f32 v[136:137], v[108:109], s[74:75] op_sel_hi:[1,0]
	v_pk_mul_f32 v[140:141], v[112:113], s[74:75] op_sel_hi:[1,0]
	v_pk_mul_f32 v[138:139], v[110:111], s[74:75] op_sel_hi:[1,0]
	v_pk_mul_f32 v[142:143], v[114:115], s[74:75] op_sel_hi:[1,0]
	v_pk_fma_f32 v[120:121], v[136:137], v[120:121], v[104:105]
	v_pk_fma_f32 v[104:105], v[136:137], v[124:125], v[104:105]
	v_pk_fma_f32 v[122:123], v[138:139], v[122:123], v[106:107]
	v_pk_fma_f32 v[106:107], v[138:139], v[126:127], v[106:107]
	v_pk_fma_f32 v[120:121], v[140:141], v[124:125], v[120:121]
	v_pk_fma_f32 v[104:105], v[112:113], v[128:129], v[104:105]
	v_pk_fma_f32 v[122:123], v[142:143], v[126:127], v[122:123]
	v_pk_fma_f32 v[106:107], v[114:115], v[130:131], v[106:107]
	v_pk_fma_f32 v[120:121], v[116:117], v[128:129], v[120:121]
	v_pk_fma_f32 v[104:105], v[116:117], v[132:133], v[104:105]
	v_pk_fma_f32 v[122:123], v[118:119], v[130:131], v[122:123]
	v_pk_fma_f32 v[106:107], v[118:119], v[134:135], v[106:107]
	v_pk_mul_f32 v[144:145], v[24:25], s[68:69] op_sel_hi:[1,0]
	v_pk_fma_f32 v[144:145], v[144:145], v[24:25], s[70:71] op_sel_hi:[1,1,0]
	v_pk_mul_f32 v[144:145], v[24:25], v[144:145]
	v_pk_mul_f32 v[144:145], v[144:145], s[72:73] op_sel_hi:[1,0]
	v_exp_f32_e32 v144, v144
	v_exp_f32_e32 v145, v145
	s_nop 0
	v_pk_add_f32 v[144:145], v[144:145], 1.0 op_sel_hi:[1,0]
	v_rcp_f32_e32 v144, v144
	v_rcp_f32_e32 v145, v145
	s_nop 0
	v_pk_mul_f32 v[144:145], v[24:25], v[144:145]
	v_pk_mul_f32 v[144:145], v[144:145], v[88:89]
	v_cvt_pk_bf16_f32 v150, v144, v145
	v_pk_mul_f32 v[144:145], v[26:27], s[68:69] op_sel_hi:[1,0]
	v_pk_fma_f32 v[144:145], v[144:145], v[26:27], s[70:71] op_sel_hi:[1,1,0]
	v_pk_mul_f32 v[144:145], v[26:27], v[144:145]
	v_pk_mul_f32 v[144:145], v[144:145], s[72:73] op_sel_hi:[1,0]
	v_exp_f32_e32 v144, v144
	v_exp_f32_e32 v145, v145
	s_nop 0
	v_pk_add_f32 v[144:145], v[144:145], 1.0 op_sel_hi:[1,0]
	v_rcp_f32_e32 v144, v144
	v_rcp_f32_e32 v145, v145
	s_nop 0
	v_pk_mul_f32 v[144:145], v[26:27], v[144:145]
	v_pk_mul_f32 v[144:145], v[144:145], v[90:91]
	v_cvt_pk_bf16_f32 v151, v144, v145
	v_pk_mul_f32 v[144:145], v[56:57], s[68:69] op_sel_hi:[1,0]
	v_pk_fma_f32 v[144:145], v[144:145], v[56:57], s[70:71] op_sel_hi:[1,1,0]
	v_pk_mul_f32 v[144:145], v[56:57], v[144:145]
	v_pk_mul_f32 v[144:145], v[144:145], s[72:73] op_sel_hi:[1,0]
	v_exp_f32_e32 v144, v144
	v_exp_f32_e32 v145, v145
	s_nop 0
	v_pk_add_f32 v[144:145], v[144:145], 1.0 op_sel_hi:[1,0]
	v_rcp_f32_e32 v144, v144
	v_rcp_f32_e32 v145, v145
	s_nop 0
	v_pk_mul_f32 v[144:145], v[56:57], v[144:145]
	v_pk_mul_f32 v[144:145], v[144:145], v[120:121]
	v_cvt_pk_bf16_f32 v152, v144, v145
	v_pk_mul_f32 v[144:145], v[58:59], s[68:69] op_sel_hi:[1,0]
	v_pk_fma_f32 v[144:145], v[144:145], v[58:59], s[70:71] op_sel_hi:[1,1,0]
	v_pk_mul_f32 v[144:145], v[58:59], v[144:145]
	v_pk_mul_f32 v[144:145], v[144:145], s[72:73] op_sel_hi:[1,0]
	v_exp_f32_e32 v144, v144
	v_exp_f32_e32 v145, v145
	s_nop 0
	v_pk_add_f32 v[144:145], v[144:145], 1.0 op_sel_hi:[1,0]
	v_rcp_f32_e32 v144, v144
	v_rcp_f32_e32 v145, v145
	s_nop 0
	v_pk_mul_f32 v[144:145], v[58:59], v[144:145]
	v_pk_mul_f32 v[144:145], v[144:145], v[122:123]
	v_cvt_pk_bf16_f32 v153, v144, v145
	global_store_dwordx4 v4, v[150:153], s[90:91]
	s_nop 1
	v_pk_mul_f32 v[144:145], v[8:9], s[68:69] op_sel_hi:[1,0]
	v_pk_fma_f32 v[144:145], v[144:145], v[8:9], s[70:71] op_sel_hi:[1,1,0]
	v_pk_mul_f32 v[144:145], v[8:9], v[144:145]
	v_pk_mul_f32 v[144:145], v[144:145], s[72:73] op_sel_hi:[1,0]
	v_exp_f32_e32 v144, v144
	v_exp_f32_e32 v145, v145
	s_nop 0
	v_pk_add_f32 v[144:145], v[144:145], 1.0 op_sel_hi:[1,0]
	v_rcp_f32_e32 v144, v144
	v_rcp_f32_e32 v145, v145
	s_nop 0
	v_pk_mul_f32 v[144:145], v[8:9], v[144:145]
	v_pk_mul_f32 v[144:145], v[144:145], v[72:73]
	v_cvt_pk_bf16_f32 v150, v144, v145
	v_pk_mul_f32 v[144:145], v[10:11], s[68:69] op_sel_hi:[1,0]
	v_pk_fma_f32 v[144:145], v[144:145], v[10:11], s[70:71] op_sel_hi:[1,1,0]
	v_pk_mul_f32 v[144:145], v[10:11], v[144:145]
	v_pk_mul_f32 v[144:145], v[144:145], s[72:73] op_sel_hi:[1,0]
	v_exp_f32_e32 v144, v144
	v_exp_f32_e32 v145, v145
	s_nop 0
	v_pk_add_f32 v[144:145], v[144:145], 1.0 op_sel_hi:[1,0]
	v_rcp_f32_e32 v144, v144
	v_rcp_f32_e32 v145, v145
	s_nop 0
	v_pk_mul_f32 v[144:145], v[10:11], v[144:145]
	v_pk_mul_f32 v[144:145], v[144:145], v[74:75]
	v_cvt_pk_bf16_f32 v151, v144, v145
	v_pk_mul_f32 v[144:145], v[40:41], s[68:69] op_sel_hi:[1,0]
	v_pk_fma_f32 v[144:145], v[144:145], v[40:41], s[70:71] op_sel_hi:[1,1,0]
	v_pk_mul_f32 v[144:145], v[40:41], v[144:145]
	v_pk_mul_f32 v[144:145], v[144:145], s[72:73] op_sel_hi:[1,0]
	v_exp_f32_e32 v144, v144
	v_exp_f32_e32 v145, v145
	s_nop 0
	v_pk_add_f32 v[144:145], v[144:145], 1.0 op_sel_hi:[1,0]
	v_rcp_f32_e32 v144, v144
	v_rcp_f32_e32 v145, v145
	s_nop 0
	v_pk_mul_f32 v[144:145], v[40:41], v[144:145]
	v_pk_mul_f32 v[144:145], v[144:145], v[104:105]
	v_cvt_pk_bf16_f32 v152, v144, v145
	v_pk_mul_f32 v[144:145], v[42:43], s[68:69] op_sel_hi:[1,0]
	v_pk_fma_f32 v[144:145], v[144:145], v[42:43], s[70:71] op_sel_hi:[1,1,0]
	v_pk_mul_f32 v[144:145], v[42:43], v[144:145]
	v_pk_mul_f32 v[144:145], v[144:145], s[72:73] op_sel_hi:[1,0]
	v_exp_f32_e32 v144, v144
	v_exp_f32_e32 v145, v145
	s_nop 0
	v_pk_add_f32 v[144:145], v[144:145], 1.0 op_sel_hi:[1,0]
	v_rcp_f32_e32 v144, v144
	v_rcp_f32_e32 v145, v145
	s_nop 0
	v_pk_mul_f32 v[144:145], v[42:43], v[144:145]
	v_pk_mul_f32 v[144:145], v[144:145], v[106:107]
	v_cvt_pk_bf16_f32 v153, v144, v145
	global_store_dwordx4 v4, v[150:153], s[92:93]
	s_nop 1
	v_readfirstlane_b32 s59, v0
	s_lshr_b32 s59, s59, 6
	s_cmp_gt_u32 s59, 2
	s_cbranch_scc1 .Lhook_done
	v_add_u32_e32 v2, 0x4000, v2
	v_add_u32_e32 v3, 0x4000, v3
	v_add_u32_e32 v4, 0x2000, v4
	global_load_dwordx4 v[8:11], v2, s[66:67]
	global_load_dwordx4 v[12:15], v2, s[38:39]
	global_load_dwordx4 v[16:19], v2, s[40:41]
	global_load_dwordx4 v[20:23], v2, s[42:43]
	global_load_dwordx4 v[24:27], v2, s[82:83]
	global_load_dwordx4 v[28:31], v2, s[84:85]
	global_load_dwordx4 v[32:35], v2, s[86:87]
	global_load_dwordx4 v[36:39], v2, s[88:89]
	global_load_dwordx4 v[40:43], v2, s[66:67] offset:16
	global_load_dwordx4 v[44:47], v2, s[38:39] offset:16
	global_load_dwordx4 v[48:51], v2, s[40:41] offset:16
	global_load_dwordx4 v[52:55], v2, s[42:43] offset:16
	global_load_dwordx4 v[56:59], v2, s[82:83] offset:16
	global_load_dwordx4 v[60:63], v2, s[84:85] offset:16
	global_load_dwordx4 v[64:67], v2, s[86:87] offset:16
	global_load_dwordx4 v[68:71], v2, s[88:89] offset:16
	global_load_dwordx4 v[72:75], v3, s[66:67]
	global_load_dwordx4 v[76:79], v3, s[38:39]
	global_load_dwordx4 v[80:83], v3, s[40:41]
	global_load_dwordx4 v[84:87], v3, s[42:43]
	global_load_dwordx4 v[88:91], v3, s[82:83]
	global_load_dwordx4 v[92:95], v3, s[84:85]
	global_load_dwordx4 v[96:99], v3, s[86:87]
	global_load_dwordx4 v[100:103], v3, s[88:89]
	global_load_dwordx4 v[104:107], v3, s[66:67] offset:16
	global_load_dwordx4 v[108:111], v3, s[38:39] offset:16
	global_load_dwordx4 v[112:115], v3, s[40:41] offset:16
	global_load_dwordx4 v[116:119], v3, s[42:43] offset:16
	global_load_dwordx4 v[120:123], v3, s[82:83] offset:16
	global_load_dwordx4 v[124:127], v3, s[84:85] offset:16
	global_load_dwordx4 v[128:131], v3, s[86:87] offset:16
	global_load_dwordx4 v[132:135], v3, s[88:89] offset:16
	s_waitcnt vmcnt(0)
	v_pk_mul_f32 v[136:137], v[12:13], s[74:75] op_sel_hi:[1,0]
	v_pk_mul_f32 v[140:141], v[16:17], s[74:75] op_sel_hi:[1,0]
	v_pk_mul_f32 v[138:139], v[14:15], s[74:75] op_sel_hi:[1,0]
	v_pk_mul_f32 v[142:143], v[18:19], s[74:75] op_sel_hi:[1,0]
	v_pk_fma_f32 v[24:25], v[136:137], v[24:25], v[8:9]
	v_pk_fma_f32 v[8:9], v[136:137], v[28:29], v[8:9]
	v_pk_fma_f32 v[26:27], v[138:139], v[26:27], v[10:11]
	v_pk_fma_f32 v[10:11], v[138:139], v[30:31], v[10:11]
	v_pk_fma_f32 v[24:25], v[140:141], v[28:29], v[24:25]
	v_pk_fma_f32 v[8:9], v[16:17], v[32:33], v[8:9]
	v_pk_fma_f32 v[26:27], v[142:143], v[30:31], v[26:27]
	v_pk_fma_f32 v[10:11], v[18:19], v[34:35], v[10:11]
	v_pk_fma_f32 v[24:25], v[20:21], v[32:33], v[24:25]
	v_pk_fma_f32 v[8:9], v[20:21], v[36:37], v[8:9]
	v_pk_fma_f32 v[26:27], v[22:23], v[34:35], v[26:27]
	v_pk_fma_f32 v[10:11], v[22:23], v[38:39], v[10:11]
	v_pk_mul_f32 v[136:137], v[44:45], s[74:75] op_sel_hi:[1,0]
	v_pk_mul_f32 v[140:141], v[48:49], s[74:75] op_sel_hi:[1,0]
	v_pk_mul_f32 v[138:139], v[46:47], s[74:75] op_sel_hi:[1,0]
	v_pk_mul_f32 v[142:143], v[50:51], s[74:75] op_sel_hi:[1,0]
	v_pk_fma_f32 v[56:57], v[136:137], v[56:57], v[40:41]
	v_pk_fma_f32 v[40:41], v[136:137], v[60:61], v[40:41]
	v_pk_fma_f32 v[58:59], v[138:139], v[58:59], v[42:43]
	v_pk_fma_f32 v[42:43], v[138:139], v[62:63], v[42:43]
	v_pk_fma_f32 v[56:57], v[140:141], v[60:61], v[56:57]
	v_pk_fma_f32 v[40:41], v[48:49], v[64:65], v[40:41]
	v_pk_fma_f32 v[58:59], v[142:143], v[62:63], v[58:59]
	v_pk_fma_f32 v[42:43], v[50:51], v[66:67], v[42:43]
	v_pk_fma_f32 v[56:57], v[52:53], v[64:65], v[56:57]
	v_pk_fma_f32 v[40:41], v[52:53], v[68:69], v[40:41]
	v_pk_fma_f32 v[58:59], v[54:55], v[66:67], v[58:59]
	v_pk_fma_f32 v[42:43], v[54:55], v[70:71], v[42:43]
	v_pk_mul_f32 v[136:137], v[76:77], s[74:75] op_sel_hi:[1,0]
	v_pk_mul_f32 v[140:141], v[80:81], s[74:75] op_sel_hi:[1,0]
	v_pk_mul_f32 v[138:139], v[78:79], s[74:75] op_sel_hi:[1,0]
	v_pk_mul_f32 v[142:143], v[82:83], s[74:75] op_sel_hi:[1,0]
	v_pk_fma_f32 v[88:89], v[136:137], v[88:89], v[72:73]
	v_pk_fma_f32 v[72:73], v[136:137], v[92:93], v[72:73]
	v_pk_fma_f32 v[90:91], v[138:139], v[90:91], v[74:75]
	v_pk_fma_f32 v[74:75], v[138:139], v[94:95], v[74:75]
	v_pk_fma_f32 v[88:89], v[140:141], v[92:93], v[88:89]
	v_pk_fma_f32 v[72:73], v[80:81], v[96:97], v[72:73]
	v_pk_fma_f32 v[90:91], v[142:143], v[94:95], v[90:91]
	v_pk_fma_f32 v[74:75], v[82:83], v[98:99], v[74:75]
	v_pk_fma_f32 v[88:89], v[84:85], v[96:97], v[88:89]
	v_pk_fma_f32 v[72:73], v[84:85], v[100:101], v[72:73]
	v_pk_fma_f32 v[90:91], v[86:87], v[98:99], v[90:91]
	v_pk_fma_f32 v[74:75], v[86:87], v[102:103], v[74:75]
	v_pk_mul_f32 v[136:137], v[108:109], s[74:75] op_sel_hi:[1,0]
	v_pk_mul_f32 v[140:141], v[112:113], s[74:75] op_sel_hi:[1,0]
	v_pk_mul_f32 v[138:139], v[110:111], s[74:75] op_sel_hi:[1,0]
	v_pk_mul_f32 v[142:143], v[114:115], s[74:75] op_sel_hi:[1,0]
	v_pk_fma_f32 v[120:121], v[136:137], v[120:121], v[104:105]
	v_pk_fma_f32 v[104:105], v[136:137], v[124:125], v[104:105]
	v_pk_fma_f32 v[122:123], v[138:139], v[122:123], v[106:107]
	v_pk_fma_f32 v[106:107], v[138:139], v[126:127], v[106:107]
	v_pk_fma_f32 v[120:121], v[140:141], v[124:125], v[120:121]
	v_pk_fma_f32 v[104:105], v[112:113], v[128:129], v[104:105]
	v_pk_fma_f32 v[122:123], v[142:143], v[126:127], v[122:123]
	v_pk_fma_f32 v[106:107], v[114:115], v[130:131], v[106:107]
	v_pk_fma_f32 v[120:121], v[116:117], v[128:129], v[120:121]
	v_pk_fma_f32 v[104:105], v[116:117], v[132:133], v[104:105]
	v_pk_fma_f32 v[122:123], v[118:119], v[130:131], v[122:123]
	v_pk_fma_f32 v[106:107], v[118:119], v[134:135], v[106:107]
	v_pk_mul_f32 v[144:145], v[24:25], s[68:69] op_sel_hi:[1,0]
	v_pk_fma_f32 v[144:145], v[144:145], v[24:25], s[70:71] op_sel_hi:[1,1,0]
	v_pk_mul_f32 v[144:145], v[24:25], v[144:145]
	v_pk_mul_f32 v[144:145], v[144:145], s[72:73] op_sel_hi:[1,0]
	v_exp_f32_e32 v144, v144
	v_exp_f32_e32 v145, v145
	s_nop 0
	v_pk_add_f32 v[144:145], v[144:145], 1.0 op_sel_hi:[1,0]
	v_rcp_f32_e32 v144, v144
	v_rcp_f32_e32 v145, v145
	s_nop 0
	v_pk_mul_f32 v[144:145], v[24:25], v[144:145]
	v_pk_mul_f32 v[144:145], v[144:145], v[88:89]
	v_cvt_pk_bf16_f32 v150, v144, v145
	v_pk_mul_f32 v[144:145], v[26:27], s[68:69] op_sel_hi:[1,0]
	v_pk_fma_f32 v[144:145], v[144:145], v[26:27], s[70:71] op_sel_hi:[1,1,0]
	v_pk_mul_f32 v[144:145], v[26:27], v[144:145]
	v_pk_mul_f32 v[144:145], v[144:145], s[72:73] op_sel_hi:[1,0]
	v_exp_f32_e32 v144, v144
	v_exp_f32_e32 v145, v145
	s_nop 0
	v_pk_add_f32 v[144:145], v[144:145], 1.0 op_sel_hi:[1,0]
	v_rcp_f32_e32 v144, v144
	v_rcp_f32_e32 v145, v145
	s_nop 0
	v_pk_mul_f32 v[144:145], v[26:27], v[144:145]
	v_pk_mul_f32 v[144:145], v[144:145], v[90:91]
	v_cvt_pk_bf16_f32 v151, v144, v145
	v_pk_mul_f32 v[144:145], v[56:57], s[68:69] op_sel_hi:[1,0]
	v_pk_fma_f32 v[144:145], v[144:145], v[56:57], s[70:71] op_sel_hi:[1,1,0]
	v_pk_mul_f32 v[144:145], v[56:57], v[144:145]
	v_pk_mul_f32 v[144:145], v[144:145], s[72:73] op_sel_hi:[1,0]
	v_exp_f32_e32 v144, v144
	v_exp_f32_e32 v145, v145
	s_nop 0
	v_pk_add_f32 v[144:145], v[144:145], 1.0 op_sel_hi:[1,0]
	v_rcp_f32_e32 v144, v144
	v_rcp_f32_e32 v145, v145
	s_nop 0
	v_pk_mul_f32 v[144:145], v[56:57], v[144:145]
	v_pk_mul_f32 v[144:145], v[144:145], v[120:121]
	v_cvt_pk_bf16_f32 v152, v144, v145
	v_pk_mul_f32 v[144:145], v[58:59], s[68:69] op_sel_hi:[1,0]
	v_pk_fma_f32 v[144:145], v[144:145], v[58:59], s[70:71] op_sel_hi:[1,1,0]
	v_pk_mul_f32 v[144:145], v[58:59], v[144:145]
	v_pk_mul_f32 v[144:145], v[144:145], s[72:73] op_sel_hi:[1,0]
	v_exp_f32_e32 v144, v144
	v_exp_f32_e32 v145, v145
	s_nop 0
	v_pk_add_f32 v[144:145], v[144:145], 1.0 op_sel_hi:[1,0]
	v_rcp_f32_e32 v144, v144
	v_rcp_f32_e32 v145, v145
	s_nop 0
	v_pk_mul_f32 v[144:145], v[58:59], v[144:145]
	v_pk_mul_f32 v[144:145], v[144:145], v[122:123]
	v_cvt_pk_bf16_f32 v153, v144, v145
	global_store_dwordx4 v4, v[150:153], s[90:91]
	s_nop 1
	v_pk_mul_f32 v[144:145], v[8:9], s[68:69] op_sel_hi:[1,0]
	v_pk_fma_f32 v[144:145], v[144:145], v[8:9], s[70:71] op_sel_hi:[1,1,0]
	v_pk_mul_f32 v[144:145], v[8:9], v[144:145]
	v_pk_mul_f32 v[144:145], v[144:145], s[72:73] op_sel_hi:[1,0]
	v_exp_f32_e32 v144, v144
	v_exp_f32_e32 v145, v145
	s_nop 0
	v_pk_add_f32 v[144:145], v[144:145], 1.0 op_sel_hi:[1,0]
	v_rcp_f32_e32 v144, v144
	v_rcp_f32_e32 v145, v145
	s_nop 0
	v_pk_mul_f32 v[144:145], v[8:9], v[144:145]
	v_pk_mul_f32 v[144:145], v[144:145], v[72:73]
	v_cvt_pk_bf16_f32 v150, v144, v145
	v_pk_mul_f32 v[144:145], v[10:11], s[68:69] op_sel_hi:[1,0]
	v_pk_fma_f32 v[144:145], v[144:145], v[10:11], s[70:71] op_sel_hi:[1,1,0]
	v_pk_mul_f32 v[144:145], v[10:11], v[144:145]
	v_pk_mul_f32 v[144:145], v[144:145], s[72:73] op_sel_hi:[1,0]
	v_exp_f32_e32 v144, v144
	v_exp_f32_e32 v145, v145
	s_nop 0
	v_pk_add_f32 v[144:145], v[144:145], 1.0 op_sel_hi:[1,0]
	v_rcp_f32_e32 v144, v144
	v_rcp_f32_e32 v145, v145
	s_nop 0
	v_pk_mul_f32 v[144:145], v[10:11], v[144:145]
	v_pk_mul_f32 v[144:145], v[144:145], v[74:75]
	v_cvt_pk_bf16_f32 v151, v144, v145
	v_pk_mul_f32 v[144:145], v[40:41], s[68:69] op_sel_hi:[1,0]
	v_pk_fma_f32 v[144:145], v[144:145], v[40:41], s[70:71] op_sel_hi:[1,1,0]
	v_pk_mul_f32 v[144:145], v[40:41], v[144:145]
	v_pk_mul_f32 v[144:145], v[144:145], s[72:73] op_sel_hi:[1,0]
	v_exp_f32_e32 v144, v144
	v_exp_f32_e32 v145, v145
	s_nop 0
	v_pk_add_f32 v[144:145], v[144:145], 1.0 op_sel_hi:[1,0]
	v_rcp_f32_e32 v144, v144
	v_rcp_f32_e32 v145, v145
	s_nop 0
	v_pk_mul_f32 v[144:145], v[40:41], v[144:145]
	v_pk_mul_f32 v[144:145], v[144:145], v[104:105]
	v_cvt_pk_bf16_f32 v152, v144, v145
	v_pk_mul_f32 v[144:145], v[42:43], s[68:69] op_sel_hi:[1,0]
	v_pk_fma_f32 v[144:145], v[144:145], v[42:43], s[70:71] op_sel_hi:[1,1,0]
	v_pk_mul_f32 v[144:145], v[42:43], v[144:145]
	v_pk_mul_f32 v[144:145], v[144:145], s[72:73] op_sel_hi:[1,0]
	v_exp_f32_e32 v144, v144
	v_exp_f32_e32 v145, v145
	s_nop 0
	v_pk_add_f32 v[144:145], v[144:145], 1.0 op_sel_hi:[1,0]
	v_rcp_f32_e32 v144, v144
	v_rcp_f32_e32 v145, v145
	s_nop 0
	v_pk_mul_f32 v[144:145], v[42:43], v[144:145]
	v_pk_mul_f32 v[144:145], v[144:145], v[106:107]
	v_cvt_pk_bf16_f32 v153, v144, v145
	global_store_dwordx4 v4, v[150:153], s[92:93]
	s_nop 1
